# opt9
# baseline (speedup 1.0000x reference)
; #define WAIT_V(n) asm volatile("s_waitcnt vmcnt(" #n ")" ::: "memory")
; #define BAR __builtin_amdgcn_s_barrier()
; template <bool PEEL = false>
; __device__ __forceinline__ void gemm_tile(f32x4 (&acc)[2][2][4][2], const u16* __restrict__ A, int lda,
;                                           const u16* __restrict__ B, int K) {
;     ...
;   STAGE_B(SB(0, 0), 0, 0); STAGE_A(SA(0, 0), 0, 0);
;   STAGE_B(SB(0, 1), 1, 0); STAGE_A(SA(0, 1), 1, 0);
;   if (wr == 1) BAR;
;   WAIT_V(4); BAR;
;   STAGE_B(SB(1, 0), 0, 1); STAGE_A(SA(1, 0), 0, 1); STAGE_B(SB(1, 1), 1, 1);
; __device__ __forceinline__ void gemm_ffn_up(const u16* __restrict__ A, const u16* __restrict__ Wt, u16* __restrict__ hid) {
;     ...
;   for (int nt = 0; nt < 22; ++nt) {
;     f32x4 acc[2][2][4][2];
;     gemm_tile<true>(acc, A, 1024, Wt + (size_t)nt * 256 * 1024, 1024);
.LBB0_135:
	s_or_b64 exec, exec, s[0:1]
	s_cmp_eq_u32 s8, 21
	s_cbranch_scc1 .Lpf1_skip
	s_mov_b32 m0, s85
	s_nop 0
	buffer_load_dwordx4 v244, s[4:7], s17 offen lds
	s_mov_b32 m0, s86
	s_nop 0
	buffer_load_dwordx4 v244, s[4:7], s18 offen lds

.LBB0_139:
	ds_read_b128 v[144:147], v139
	ds_read_b128 v[148:151], v139 offset:1024
	ds_read_b128 v[152:155], v139 offset:2048
	ds_read_b128 v[156:159], v139 offset:3072
	s_mov_b32 m0, s88
	s_add_i32 s91, s90, 0xfffdff00
	ds_read_b128 v[160:163], v134
	ds_read_b128 v[164:167], v134 offset:1024
	ds_read_b128 v[168:171], v135
	ds_read_b128 v[172:175], v135 offset:1024
	ds_read_b128 v[176:179], v136
	ds_read_b128 v[180:183], v136 offset:1024
	ds_read_b128 v[184:187], v137
	ds_read_b128 v[188:191], v137 offset:1024
	buffer_load_dwordx4 v138, s[56:59], s91 offen lds
	s_add_i32 s91, s90, 0xffffff00
	s_mov_b32 m0, s87
	s_nop 0
	buffer_load_dwordx4 v138, s[56:59], s91 offen lds
	s_waitcnt lgkmcnt(8)
	s_barrier
	s_waitcnt lgkmcnt(0)
	s_setprio 1
	s_waitcnt lgkmcnt(7)
	v_mfma_f32_16x16x32_bf16 v[28:31], v[160:163], v[144:147], v[28:31]
	v_mfma_f32_16x16x32_bf16 v[24:27], v[160:163], v[152:155], v[24:27]
	s_waitcnt lgkmcnt(5)
	v_mfma_f32_16x16x32_bf16 v[20:23], v[168:171], v[144:147], v[20:23]
	v_mfma_f32_16x16x32_bf16 v[16:19], v[168:171], v[152:155], v[16:19]
	s_waitcnt lgkmcnt(3)
	v_mfma_f32_16x16x32_bf16 v[12:15], v[176:179], v[144:147], v[12:15]
	v_mfma_f32_16x16x32_bf16 v[8:11], v[176:179], v[152:155], v[8:11]
	s_waitcnt lgkmcnt(1)
	v_mfma_f32_16x16x32_bf16 v[4:7], v[184:187], v[144:147], v[4:7]
	v_mfma_f32_16x16x32_bf16 v[0:3], v[184:187], v[152:155], v[0:3]
	v_mfma_f32_16x16x32_bf16 v[28:31], v[164:167], v[148:151], v[28:31]
	v_mfma_f32_16x16x32_bf16 v[24:27], v[164:167], v[156:159], v[24:27]
	v_mfma_f32_16x16x32_bf16 v[20:23], v[172:175], v[148:151], v[20:23]
	v_mfma_f32_16x16x32_bf16 v[16:19], v[172:175], v[156:159], v[16:19]
	v_mfma_f32_16x16x32_bf16 v[12:15], v[180:183], v[148:151], v[12:15]
	v_mfma_f32_16x16x32_bf16 v[8:11], v[180:183], v[156:159], v[8:11]
	s_waitcnt lgkmcnt(0)
	v_mfma_f32_16x16x32_bf16 v[4:7], v[188:191], v[148:151], v[4:7]
	v_mfma_f32_16x16x32_bf16 v[0:3], v[188:191], v[156:159], v[0:3]
	s_setprio 0
	s_barrier
	s_mov_b32 m0, s74
	s_add_i32 s91, s90, 0xfff9ff80
	ds_read_b128 v[192:195], v140
	ds_read_b128 v[196:199], v140 offset:1024
	ds_read_b128 v[200:203], v140 offset:2048
	ds_read_b128 v[204:207], v140 offset:3072
	buffer_load_dwordx4 v138, s[4:7], s91 offen lds
	s_add_i32 s92, s90, 0xfffbff80
	s_mov_b32 m0, s75
	s_nop 0
	buffer_load_dwordx4 v138, s[4:7], s92 offen lds
	s_barrier
	s_waitcnt lgkmcnt(0)
	s_setprio 1
	s_waitcnt lgkmcnt(3)
	v_mfma_f32_16x16x32_bf16 v[60:63], v[160:163], v[192:195], v[60:63]
	s_waitcnt lgkmcnt(1)
	v_mfma_f32_16x16x32_bf16 v[56:59], v[160:163], v[200:203], v[56:59]
	v_mfma_f32_16x16x32_bf16 v[52:55], v[168:171], v[192:195], v[52:55]
	v_mfma_f32_16x16x32_bf16 v[48:51], v[168:171], v[200:203], v[48:51]
	v_mfma_f32_16x16x32_bf16 v[44:47], v[176:179], v[192:195], v[44:47]
	v_mfma_f32_16x16x32_bf16 v[40:43], v[176:179], v[200:203], v[40:43]
	v_mfma_f32_16x16x32_bf16 v[36:39], v[184:187], v[192:195], v[36:39]
	v_mfma_f32_16x16x32_bf16 v[32:35], v[184:187], v[200:203], v[32:35]
	v_mfma_f32_16x16x32_bf16 v[60:63], v[164:167], v[196:199], v[60:63]
	s_waitcnt lgkmcnt(0)
	v_mfma_f32_16x16x32_bf16 v[56:59], v[164:167], v[204:207], v[56:59]
	v_mfma_f32_16x16x32_bf16 v[52:55], v[172:175], v[196:199], v[52:55]
	v_mfma_f32_16x16x32_bf16 v[48:51], v[172:175], v[204:207], v[48:51]
	v_mfma_f32_16x16x32_bf16 v[44:47], v[180:183], v[196:199], v[44:47]
	v_mfma_f32_16x16x32_bf16 v[40:43], v[180:183], v[204:207], v[40:43]
	v_mfma_f32_16x16x32_bf16 v[36:39], v[188:191], v[196:199], v[36:39]
	v_mfma_f32_16x16x32_bf16 v[32:35], v[188:191], v[204:207], v[32:35]
	s_setprio 0
	s_mov_b32 m0, s71
	s_barrier
	ds_read_b128 v[160:163], v134 offset:16384
	ds_read_b128 v[164:167], v134 offset:17408
	ds_read_b128 v[168:171], v135 offset:16384
	ds_read_b128 v[172:175], v135 offset:17408
	ds_read_b128 v[176:179], v136 offset:16384
	ds_read_b128 v[180:183], v136 offset:17408
	ds_read_b128 v[184:187], v137 offset:16384
	ds_read_b128 v[188:191], v137 offset:17408
	buffer_load_dwordx4 v138, s[56:59], s91 offen lds
	s_mov_b32 m0, s76
	s_nop 0
	buffer_load_dwordx4 v138, s[56:59], s92 offen lds
	s_barrier
	s_waitcnt lgkmcnt(0)
	s_setprio 1
	s_waitcnt lgkmcnt(7)
	v_mfma_f32_16x16x32_bf16 v[92:95], v[160:163], v[144:147], v[92:95]
	v_mfma_f32_16x16x32_bf16 v[88:91], v[160:163], v[152:155], v[88:91]
	s_waitcnt lgkmcnt(5)
	v_mfma_f32_16x16x32_bf16 v[84:87], v[168:171], v[144:147], v[84:87]
	v_mfma_f32_16x16x32_bf16 v[80:83], v[168:171], v[152:155], v[80:83]
	s_waitcnt lgkmcnt(3)
	v_mfma_f32_16x16x32_bf16 v[76:79], v[176:179], v[144:147], v[76:79]
	v_mfma_f32_16x16x32_bf16 v[72:75], v[176:179], v[152:155], v[72:75]
	s_waitcnt lgkmcnt(1)
	v_mfma_f32_16x16x32_bf16 v[68:71], v[184:187], v[144:147], v[68:71]
	v_mfma_f32_16x16x32_bf16 v[64:67], v[184:187], v[152:155], v[64:67]
	v_mfma_f32_16x16x32_bf16 v[92:95], v[164:167], v[148:151], v[92:95]
	v_mfma_f32_16x16x32_bf16 v[88:91], v[164:167], v[156:159], v[88:91]
	v_mfma_f32_16x16x32_bf16 v[84:87], v[172:175], v[148:151], v[84:87]
	v_mfma_f32_16x16x32_bf16 v[80:83], v[172:175], v[156:159], v[80:83]
	v_mfma_f32_16x16x32_bf16 v[76:79], v[180:183], v[148:151], v[76:79]
	v_mfma_f32_16x16x32_bf16 v[72:75], v[180:183], v[156:159], v[72:75]
	s_waitcnt lgkmcnt(0)
	v_mfma_f32_16x16x32_bf16 v[68:71], v[188:191], v[148:151], v[68:71]
	v_mfma_f32_16x16x32_bf16 v[64:67], v[188:191], v[156:159], v[64:67]
	s_setprio 0
	s_barrier
	s_mov_b32 m0, s78
	s_add_i32 s91, s90, 0xfffdff80
	buffer_load_dwordx4 v138, s[4:7], s91 offen lds
	s_add_i32 s92, s90, 0xffffff80
	s_mov_b32 m0, s79
	s_nop 0
	buffer_load_dwordx4 v138, s[4:7], s92 offen lds
	s_waitcnt vmcnt(6)
	s_barrier
	s_setprio 1
	v_mfma_f32_16x16x32_bf16 v[124:127], v[160:163], v[192:195], v[124:127]
	v_mfma_f32_16x16x32_bf16 v[120:123], v[160:163], v[200:203], v[120:123]
	v_mfma_f32_16x16x32_bf16 v[116:119], v[168:171], v[192:195], v[116:119]
	v_mfma_f32_16x16x32_bf16 v[112:115], v[168:171], v[200:203], v[112:115]
	v_mfma_f32_16x16x32_bf16 v[108:111], v[176:179], v[192:195], v[108:111]
	v_mfma_f32_16x16x32_bf16 v[104:107], v[176:179], v[200:203], v[104:107]
	v_mfma_f32_16x16x32_bf16 v[100:103], v[184:187], v[192:195], v[100:103]
	v_mfma_f32_16x16x32_bf16 v[96:99], v[184:187], v[200:203], v[96:99]
	v_mfma_f32_16x16x32_bf16 v[124:127], v[164:167], v[196:199], v[124:127]
	v_mfma_f32_16x16x32_bf16 v[120:123], v[164:167], v[204:207], v[120:123]
	v_mfma_f32_16x16x32_bf16 v[116:119], v[172:175], v[196:199], v[116:119]
	v_mfma_f32_16x16x32_bf16 v[112:115], v[172:175], v[204:207], v[112:115]
	v_mfma_f32_16x16x32_bf16 v[108:111], v[180:183], v[196:199], v[108:111]
	v_mfma_f32_16x16x32_bf16 v[104:107], v[180:183], v[204:207], v[104:107]
	v_mfma_f32_16x16x32_bf16 v[100:103], v[188:191], v[196:199], v[100:103]
	v_mfma_f32_16x16x32_bf16 v[96:99], v[188:191], v[204:207], v[96:99]
	s_setprio 0
	s_barrier
	ds_read_b128 v[144:147], v141
	ds_read_b128 v[148:151], v141 offset:1024
	ds_read_b128 v[152:155], v141 offset:2048
	ds_read_b128 v[156:159], v141 offset:3072
	s_mov_b32 m0, s81
	ds_read_b128 v[160:163], v134 offset:32768
	ds_read_b128 v[164:167], v134 offset:33792
	ds_read_b128 v[168:171], v135 offset:32768
	ds_read_b128 v[172:175], v135 offset:33792
	ds_read_b128 v[176:179], v136 offset:32768
	ds_read_b128 v[180:183], v136 offset:33792
	ds_read_b128 v[184:187], v137 offset:32768
	ds_read_b128 v[188:191], v137 offset:33792
	buffer_load_dwordx4 v138, s[56:59], s91 offen lds
	s_mov_b32 m0, s82
	s_nop 0
	buffer_load_dwordx4 v138, s[56:59], s92 offen lds
	s_waitcnt lgkmcnt(8)
	s_barrier
	s_waitcnt lgkmcnt(0)
	s_setprio 1
	s_waitcnt lgkmcnt(7)
	v_mfma_f32_16x16x32_bf16 v[28:31], v[160:163], v[144:147], v[28:31]
	v_mfma_f32_16x16x32_bf16 v[24:27], v[160:163], v[152:155], v[24:27]
	s_waitcnt lgkmcnt(5)
	v_mfma_f32_16x16x32_bf16 v[20:23], v[168:171], v[144:147], v[20:23]
	v_mfma_f32_16x16x32_bf16 v[16:19], v[168:171], v[152:155], v[16:19]
	s_waitcnt lgkmcnt(3)
	v_mfma_f32_16x16x32_bf16 v[12:15], v[176:179], v[144:147], v[12:15]
	v_mfma_f32_16x16x32_bf16 v[8:11], v[176:179], v[152:155], v[8:11]
	s_waitcnt lgkmcnt(1)
	v_mfma_f32_16x16x32_bf16 v[4:7], v[184:187], v[144:147], v[4:7]
	v_mfma_f32_16x16x32_bf16 v[0:3], v[184:187], v[152:155], v[0:3]
	v_mfma_f32_16x16x32_bf16 v[28:31], v[164:167], v[148:151], v[28:31]
	v_mfma_f32_16x16x32_bf16 v[24:27], v[164:167], v[156:159], v[24:27]
	v_mfma_f32_16x16x32_bf16 v[20:23], v[172:175], v[148:151], v[20:23]
	v_mfma_f32_16x16x32_bf16 v[16:19], v[172:175], v[156:159], v[16:19]
	v_mfma_f32_16x16x32_bf16 v[12:15], v[180:183], v[148:151], v[12:15]
	v_mfma_f32_16x16x32_bf16 v[8:11], v[180:183], v[156:159], v[8:11]
	s_waitcnt lgkmcnt(0)
	v_mfma_f32_16x16x32_bf16 v[4:7], v[188:191], v[148:151], v[4:7]
	v_mfma_f32_16x16x32_bf16 v[0:3], v[188:191], v[156:159], v[0:3]
	s_setprio 0
	s_barrier
	s_mov_b32 m0, s0
	s_add_i32 s91, s90, 0xfffa0000
	ds_read_b128 v[192:195], v142
	ds_read_b128 v[196:199], v142 offset:1024
	ds_read_b128 v[200:203], v142 offset:2048
	ds_read_b128 v[204:207], v142 offset:3072
	buffer_load_dwordx4 v138, s[4:7], s91 offen lds
	s_add_i32 s92, s90, 0xfffc0000
	s_mov_b32 m0, s1
	s_nop 0
	buffer_load_dwordx4 v138, s[4:7], s92 offen lds
	s_barrier
	s_waitcnt lgkmcnt(0)
	s_setprio 1
	s_waitcnt lgkmcnt(3)
	v_mfma_f32_16x16x32_bf16 v[60:63], v[160:163], v[192:195], v[60:63]
	s_waitcnt lgkmcnt(1)
	v_mfma_f32_16x16x32_bf16 v[56:59], v[160:163], v[200:203], v[56:59]
	v_mfma_f32_16x16x32_bf16 v[52:55], v[168:171], v[192:195], v[52:55]
	v_mfma_f32_16x16x32_bf16 v[48:51], v[168:171], v[200:203], v[48:51]
	v_mfma_f32_16x16x32_bf16 v[44:47], v[176:179], v[192:195], v[44:47]
	v_mfma_f32_16x16x32_bf16 v[40:43], v[176:179], v[200:203], v[40:43]
	v_mfma_f32_16x16x32_bf16 v[36:39], v[184:187], v[192:195], v[36:39]
	v_mfma_f32_16x16x32_bf16 v[32:35], v[184:187], v[200:203], v[32:35]
	v_mfma_f32_16x16x32_bf16 v[60:63], v[164:167], v[196:199], v[60:63]
	s_waitcnt lgkmcnt(0)
	v_mfma_f32_16x16x32_bf16 v[56:59], v[164:167], v[204:207], v[56:59]
	v_mfma_f32_16x16x32_bf16 v[52:55], v[172:175], v[196:199], v[52:55]
	v_mfma_f32_16x16x32_bf16 v[48:51], v[172:175], v[204:207], v[48:51]
	v_mfma_f32_16x16x32_bf16 v[44:47], v[180:183], v[196:199], v[44:47]
	v_mfma_f32_16x16x32_bf16 v[40:43], v[180:183], v[204:207], v[40:43]
	v_mfma_f32_16x16x32_bf16 v[36:39], v[188:191], v[196:199], v[36:39]
	v_mfma_f32_16x16x32_bf16 v[32:35], v[188:191], v[204:207], v[32:35]
	s_setprio 0
	s_mov_b32 m0, s83
	s_barrier
	ds_read_b128 v[160:163], v134 offset:49152
	ds_read_b128 v[164:167], v134 offset:50176
	ds_read_b128 v[168:171], v135 offset:49152
	ds_read_b128 v[172:175], v135 offset:50176
	ds_read_b128 v[176:179], v136 offset:49152
	ds_read_b128 v[180:183], v136 offset:50176
	ds_read_b128 v[184:187], v137 offset:49152
	ds_read_b128 v[188:191], v137 offset:50176
	buffer_load_dwordx4 v138, s[56:59], s91 offen lds
	s_mov_b32 m0, s84
	s_nop 0
	buffer_load_dwordx4 v138, s[56:59], s92 offen lds
	s_barrier
; #define LDA(dst, b, h)                                                                             \
;   _Pragma("unroll") for (int m = 0; m < 4; ++m) _Pragma("unroll") for (int k = 0; k < 2; ++k)      \
;       dst[m][k] = *reinterpret_cast<const bf16x8*>(SA(b, h) + lds_byte(wr * 64 + m * 16 + fr, k * 32 + fq * 8))
; #define LDB(dst, b, h)                                                                             \
;   _Pragma("unroll") for (int n = 0; n < 2; ++n) _Pragma("unroll") for (int k = 0; k < 2; ++k)      \
;       dst[n][k] = *reinterpret_cast<const bf16x8*>(SB(b, h) + lds_byte(wc * 32 + n * 16 + fr, k * 32 + fq * 8))
; #define WAIT_V(n) asm volatile("s_waitcnt vmcnt(" #n ")" ::: "memory")
; #define WAIT_L(n) asm volatile("s_waitcnt lgkmcnt(" #n ")" ::: "memory")
; #define BAR __builtin_amdgcn_s_barrier()
; template <bool PEEL = false>
; __device__ __forceinline__ void gemm_tile(f32x4 (&acc)[2][2][4][2], const u16* __restrict__ A, int lda,
;                                           const u16* __restrict__ B, int K) {
;     ...
;     for (int t = 2; t < nt - 2; t += 2) { KLOOP_BODY(t) }
;   } else {
;     for (int t = 0; t < nt - 2; t += 2) { KLOOP_BODY(t) }
;   }
;   {
;     LDB(B0, 0, 0); LDA(At, 0, 0); STAGE_A(SA(1, 1), 1, nt - 1);
;     BAR; WAIT_L(0); MMA(0, 0, At, B0); BAR;
;     LDB(B1, 0, 1); BAR; WAIT_L(0); MMA(0, 1, At, B1); BAR;
;     LDA(At, 0, 1); WAIT_V(4); BAR; WAIT_L(0); MMA(1, 0, At, B0); MMA(1, 1, At, B1); BAR;
	s_waitcnt lgkmcnt(0)
	s_setprio 1
	s_waitcnt lgkmcnt(7)
	v_mfma_f32_16x16x32_bf16 v[92:95], v[160:163], v[144:147], v[92:95]
	v_mfma_f32_16x16x32_bf16 v[88:91], v[160:163], v[152:155], v[88:91]
	s_waitcnt lgkmcnt(5)
	v_mfma_f32_16x16x32_bf16 v[84:87], v[168:171], v[144:147], v[84:87]
	v_mfma_f32_16x16x32_bf16 v[80:83], v[168:171], v[152:155], v[80:83]
	s_waitcnt lgkmcnt(3)
	v_mfma_f32_16x16x32_bf16 v[76:79], v[176:179], v[144:147], v[76:79]
	v_mfma_f32_16x16x32_bf16 v[72:75], v[176:179], v[152:155], v[72:75]
	s_waitcnt lgkmcnt(1)
	v_mfma_f32_16x16x32_bf16 v[68:71], v[184:187], v[144:147], v[68:71]
	v_mfma_f32_16x16x32_bf16 v[64:67], v[184:187], v[152:155], v[64:67]
	v_mfma_f32_16x16x32_bf16 v[92:95], v[164:167], v[148:151], v[92:95]
	v_mfma_f32_16x16x32_bf16 v[88:91], v[164:167], v[156:159], v[88:91]
	v_mfma_f32_16x16x32_bf16 v[84:87], v[172:175], v[148:151], v[84:87]
	v_mfma_f32_16x16x32_bf16 v[80:83], v[172:175], v[156:159], v[80:83]
	v_mfma_f32_16x16x32_bf16 v[76:79], v[180:183], v[148:151], v[76:79]
	v_mfma_f32_16x16x32_bf16 v[72:75], v[180:183], v[156:159], v[72:75]
	s_waitcnt lgkmcnt(0)
	v_mfma_f32_16x16x32_bf16 v[68:71], v[188:191], v[148:151], v[68:71]
	v_mfma_f32_16x16x32_bf16 v[64:67], v[188:191], v[156:159], v[64:67]
	s_setprio 0
	s_barrier
	s_add_i32 s91, s90, 0xfffe0000
	s_mov_b32 m0, s85
	s_nop 0
	buffer_load_dwordx4 v138, s[4:7], s91 offen lds
	s_mov_b32 m0, s86
	s_nop 0
	buffer_load_dwordx4 v138, s[4:7], s90 offen lds
	s_waitcnt vmcnt(6)
	s_barrier
	s_setprio 1
	v_mfma_f32_16x16x32_bf16 v[124:127], v[160:163], v[192:195], v[124:127]
	v_mfma_f32_16x16x32_bf16 v[120:123], v[160:163], v[200:203], v[120:123]
	v_mfma_f32_16x16x32_bf16 v[116:119], v[168:171], v[192:195], v[116:119]
	v_mfma_f32_16x16x32_bf16 v[112:115], v[168:171], v[200:203], v[112:115]
	v_mfma_f32_16x16x32_bf16 v[108:111], v[176:179], v[192:195], v[108:111]
	v_mfma_f32_16x16x32_bf16 v[104:107], v[176:179], v[200:203], v[104:107]
	v_mfma_f32_16x16x32_bf16 v[100:103], v[184:187], v[192:195], v[100:103]
	v_mfma_f32_16x16x32_bf16 v[96:99], v[184:187], v[200:203], v[96:99]
	v_mfma_f32_16x16x32_bf16 v[124:127], v[164:167], v[196:199], v[124:127]
	v_mfma_f32_16x16x32_bf16 v[120:123], v[164:167], v[204:207], v[120:123]
	v_mfma_f32_16x16x32_bf16 v[116:119], v[172:175], v[196:199], v[116:119]
	v_mfma_f32_16x16x32_bf16 v[112:115], v[172:175], v[204:207], v[112:115]
	v_mfma_f32_16x16x32_bf16 v[108:111], v[180:183], v[196:199], v[108:111]
	v_mfma_f32_16x16x32_bf16 v[104:107], v[180:183], v[204:207], v[104:107]
	v_mfma_f32_16x16x32_bf16 v[100:103], v[188:191], v[196:199], v[100:103]
	v_mfma_f32_16x16x32_bf16 v[96:99], v[188:191], v[204:207], v[96:99]
	s_setprio 0
	s_add_i32 s89, s89, 2
	s_addk_i32 s90, 0x100
	s_cmp_lt_u32 s89, 12
	s_barrier
	s_cbranch_scc1 .LBB0_139
	v_mov_b32_e32 v244, v138
	s_mov_b32 m0, s88
	s_mov_b32 s0, 0x40780
	ds_read_b128 v[144:147], v139
	ds_read_b128 v[148:151], v139 offset:1024
	ds_read_b128 v[152:155], v139 offset:2048
	ds_read_b128 v[156:159], v139 offset:3072
	ds_read_b128 v[160:163], v134
	ds_read_b128 v[164:167], v134 offset:1024
	ds_read_b128 v[168:171], v135
	ds_read_b128 v[172:175], v135 offset:1024
	ds_read_b128 v[176:179], v136
	ds_read_b128 v[180:183], v136 offset:1024
	ds_read_b128 v[184:187], v137
	ds_read_b128 v[188:191], v137 offset:1024
	buffer_load_dwordx4 v138, s[56:59], s0 offen lds
	s_mov_b32 s0, 0x60780
	s_mov_b32 m0, s87
	s_nop 0
	buffer_load_dwordx4 v138, s[56:59], s0 offen lds
	s_barrier
	s_waitcnt lgkmcnt(0)
	s_setprio 1
	s_waitcnt lgkmcnt(7)
	v_mfma_f32_16x16x32_bf16 v[28:31], v[160:163], v[144:147], v[28:31]
	v_mfma_f32_16x16x32_bf16 v[24:27], v[160:163], v[152:155], v[24:27]
	s_waitcnt lgkmcnt(5)
	v_mfma_f32_16x16x32_bf16 v[20:23], v[168:171], v[144:147], v[20:23]
	v_mfma_f32_16x16x32_bf16 v[16:19], v[168:171], v[152:155], v[16:19]
	s_waitcnt lgkmcnt(3)
	v_mfma_f32_16x16x32_bf16 v[12:15], v[176:179], v[144:147], v[12:15]
	v_mfma_f32_16x16x32_bf16 v[8:11], v[176:179], v[152:155], v[8:11]
	s_waitcnt lgkmcnt(1)
	v_mfma_f32_16x16x32_bf16 v[4:7], v[184:187], v[144:147], v[4:7]
	v_mfma_f32_16x16x32_bf16 v[0:3], v[184:187], v[152:155], v[0:3]
	v_mfma_f32_16x16x32_bf16 v[28:31], v[164:167], v[148:151], v[28:31]
	v_mfma_f32_16x16x32_bf16 v[24:27], v[164:167], v[156:159], v[24:27]
	v_mfma_f32_16x16x32_bf16 v[20:23], v[172:175], v[148:151], v[20:23]
	v_mfma_f32_16x16x32_bf16 v[16:19], v[172:175], v[156:159], v[16:19]
	v_mfma_f32_16x16x32_bf16 v[12:15], v[180:183], v[148:151], v[12:15]
	v_mfma_f32_16x16x32_bf16 v[8:11], v[180:183], v[156:159], v[8:11]
	s_waitcnt lgkmcnt(0)
	v_mfma_f32_16x16x32_bf16 v[4:7], v[188:191], v[148:151], v[4:7]
	v_mfma_f32_16x16x32_bf16 v[0:3], v[188:191], v[156:159], v[0:3]
	s_setprio 0
	s_barrier
	ds_read_b128 v[192:195], v140
	ds_read_b128 v[196:199], v140 offset:1024
	ds_read_b128 v[200:203], v140 offset:2048
	ds_read_b128 v[204:207], v140 offset:3072
	s_barrier
	s_waitcnt lgkmcnt(0)
	s_setprio 1
	s_waitcnt lgkmcnt(3)
	v_mfma_f32_16x16x32_bf16 v[60:63], v[160:163], v[192:195], v[60:63]
	s_waitcnt lgkmcnt(1)
	v_mfma_f32_16x16x32_bf16 v[56:59], v[160:163], v[200:203], v[56:59]
	v_mfma_f32_16x16x32_bf16 v[52:55], v[168:171], v[192:195], v[52:55]
	v_mfma_f32_16x16x32_bf16 v[48:51], v[168:171], v[200:203], v[48:51]
	v_mfma_f32_16x16x32_bf16 v[44:47], v[176:179], v[192:195], v[44:47]
	v_mfma_f32_16x16x32_bf16 v[40:43], v[176:179], v[200:203], v[40:43]
	v_mfma_f32_16x16x32_bf16 v[36:39], v[184:187], v[192:195], v[36:39]
	v_mfma_f32_16x16x32_bf16 v[32:35], v[184:187], v[200:203], v[32:35]
	v_mfma_f32_16x16x32_bf16 v[60:63], v[164:167], v[196:199], v[60:63]
	s_waitcnt lgkmcnt(0)
	v_mfma_f32_16x16x32_bf16 v[56:59], v[164:167], v[204:207], v[56:59]
	v_mfma_f32_16x16x32_bf16 v[52:55], v[172:175], v[196:199], v[52:55]
	v_mfma_f32_16x16x32_bf16 v[48:51], v[172:175], v[204:207], v[48:51]
	v_mfma_f32_16x16x32_bf16 v[44:47], v[180:183], v[196:199], v[44:47]
	v_mfma_f32_16x16x32_bf16 v[40:43], v[180:183], v[204:207], v[40:43]
	v_mfma_f32_16x16x32_bf16 v[36:39], v[188:191], v[196:199], v[36:39]
	v_mfma_f32_16x16x32_bf16 v[32:35], v[188:191], v[204:207], v[32:35]
	s_setprio 0
	s_barrier
	ds_read_b128 v[160:163], v134 offset:16384
	ds_read_b128 v[164:167], v134 offset:17408
	ds_read_b128 v[168:171], v135 offset:16384
	ds_read_b128 v[172:175], v135 offset:17408
	ds_read_b128 v[176:179], v136 offset:16384
	ds_read_b128 v[180:183], v136 offset:17408
	ds_read_b128 v[184:187], v137 offset:16384
	ds_read_b128 v[188:191], v137 offset:17408
	s_cmp_eq_u32 s8, 21
	s_cbranch_scc1 .Lt1_a_last
	s_add_u32 s4, s4, 0x80000
	s_addc_u32 s5, s5, 0
	s_mov_b32 m0, s74
	s_nop 0
	buffer_load_dwordx4 v244, s[4:7], 0 offen lds
	s_mov_b32 m0, s75
	s_nop 0
	buffer_load_dwordx4 v244, s[4:7], s63 offen lds
	s_mov_b32 m0, s71
	s_nop 0
	buffer_load_dwordx4 v244, s[56:59], 0 offen lds
	s_mov_b32 m0, s76
	s_nop 0
	buffer_load_dwordx4 v244, s[56:59], s63 offen lds
	s_waitcnt vmcnt(8)
	s_branch .Lt1_a_join

; #define LDA(dst, b, h)                                                                             \
;   _Pragma("unroll") for (int m = 0; m < 4; ++m) _Pragma("unroll") for (int k = 0; k < 2; ++k)      \
;       dst[m][k] = *reinterpret_cast<const bf16x8*>(SA(b, h) + lds_byte(wr * 64 + m * 16 + fr, k * 32 + fq * 8))
; #define LDB(dst, b, h)                                                                             \
;   _Pragma("unroll") for (int n = 0; n < 2; ++n) _Pragma("unroll") for (int k = 0; k < 2; ++k)      \
;       dst[n][k] = *reinterpret_cast<const bf16x8*>(SB(b, h) + lds_byte(wc * 32 + n * 16 + fr, k * 32 + fq * 8))
; #define WAIT_V(n) asm volatile("s_waitcnt vmcnt(" #n ")" ::: "memory")
; #define WAIT_L(n) asm volatile("s_waitcnt lgkmcnt(" #n ")" ::: "memory")
; #define BAR __builtin_amdgcn_s_barrier()
; template <bool PEEL = false>
; __device__ __forceinline__ void gemm_tile(f32x4 (&acc)[2][2][4][2], const u16* __restrict__ A, int lda,
;                                           const u16* __restrict__ B, int K) {
;     ...
;     LDA(At, 0, 1); WAIT_V(4); BAR; WAIT_L(0); MMA(1, 0, At, B0); MMA(1, 1, At, B1); BAR;
;   }
;   {
;     LDB(B0, 1, 0); LDA(At, 1, 0); WAIT_V(2); BAR; WAIT_L(0); MMA(0, 0, At, B0); BAR;
;     LDB(B1, 1, 1); WAIT_V(0); BAR; WAIT_L(0); MMA(0, 1, At, B1); BAR;
.Lt1_a_join:
	s_barrier
	s_waitcnt lgkmcnt(0)
	s_setprio 1
	s_waitcnt lgkmcnt(7)
	v_mfma_f32_16x16x32_bf16 v[92:95], v[160:163], v[144:147], v[92:95]
	v_mfma_f32_16x16x32_bf16 v[88:91], v[160:163], v[152:155], v[88:91]
	s_waitcnt lgkmcnt(5)
	v_mfma_f32_16x16x32_bf16 v[84:87], v[168:171], v[144:147], v[84:87]
	v_mfma_f32_16x16x32_bf16 v[80:83], v[168:171], v[152:155], v[80:83]
	s_waitcnt lgkmcnt(3)
	v_mfma_f32_16x16x32_bf16 v[76:79], v[176:179], v[144:147], v[76:79]
	v_mfma_f32_16x16x32_bf16 v[72:75], v[176:179], v[152:155], v[72:75]
	s_waitcnt lgkmcnt(1)
	v_mfma_f32_16x16x32_bf16 v[68:71], v[184:187], v[144:147], v[68:71]
	v_mfma_f32_16x16x32_bf16 v[64:67], v[184:187], v[152:155], v[64:67]
	v_mfma_f32_16x16x32_bf16 v[208:211], v[164:167], v[148:151], v[92:95]
	v_mfma_f32_16x16x32_bf16 v[212:215], v[164:167], v[156:159], v[88:91]
	v_mfma_f32_16x16x32_bf16 v[216:219], v[172:175], v[148:151], v[84:87]
	v_mfma_f32_16x16x32_bf16 v[220:223], v[172:175], v[156:159], v[80:83]
	v_mfma_f32_16x16x32_bf16 v[224:227], v[180:183], v[148:151], v[76:79]
	v_mfma_f32_16x16x32_bf16 v[228:231], v[180:183], v[156:159], v[72:75]
	s_waitcnt lgkmcnt(0)
	v_mfma_f32_16x16x32_bf16 v[144:147], v[188:191], v[148:151], v[68:71]
	v_mfma_f32_16x16x32_bf16 v[148:151], v[188:191], v[156:159], v[64:67]
	s_setprio 0
	s_setprio 1
	v_mfma_f32_16x16x32_bf16 v[64:67], v[160:163], v[192:195], v[124:127]
	v_mfma_f32_16x16x32_bf16 v[152:155], v[164:167], v[196:199], v[64:67]
	v_mfma_f32_16x16x32_bf16 v[64:67], v[160:163], v[200:203], v[120:123]
	v_mfma_f32_16x16x32_bf16 v[156:159], v[164:167], v[204:207], v[64:67]
	v_mfma_f32_16x16x32_bf16 v[64:67], v[168:171], v[192:195], v[116:119]
	v_mfma_f32_16x16x32_bf16 v[160:163], v[172:175], v[196:199], v[64:67]
	v_mfma_f32_16x16x32_bf16 v[64:67], v[168:171], v[200:203], v[112:115]
	v_mfma_f32_16x16x32_bf16 v[164:167], v[172:175], v[204:207], v[64:67]
	v_mfma_f32_16x16x32_bf16 v[64:67], v[176:179], v[192:195], v[108:111]
	v_mfma_f32_16x16x32_bf16 v[168:171], v[180:183], v[196:199], v[64:67]
	v_mfma_f32_16x16x32_bf16 v[64:67], v[176:179], v[200:203], v[104:107]
	v_mfma_f32_16x16x32_bf16 v[172:175], v[180:183], v[204:207], v[64:67]
	v_mfma_f32_16x16x32_bf16 v[64:67], v[184:187], v[192:195], v[100:103]
	v_mfma_f32_16x16x32_bf16 v[176:179], v[188:191], v[196:199], v[64:67]
	v_mfma_f32_16x16x32_bf16 v[64:67], v[184:187], v[200:203], v[96:99]
	v_mfma_f32_16x16x32_bf16 v[180:183], v[188:191], v[204:207], v[64:67]
	s_setprio 0
	s_barrier
	ds_read_b128 v[184:187], v141
	ds_read_b128 v[188:191], v141 offset:1024
	ds_read_b128 v[192:195], v141 offset:2048
	ds_read_b128 v[138:141], v141 offset:3072
	ds_read_b128 v[72:75], v134 offset:32768
	ds_read_b128 v[76:79], v134 offset:33792
	ds_read_b128 v[88:91], v135 offset:32768
	ds_read_b128 v[92:95], v135 offset:33792
	ds_read_b128 v[196:199], v136 offset:32768
	ds_read_b128 v[200:203], v136 offset:33792
	ds_read_b128 v[204:207], v137 offset:32768
	ds_read_b128 v[232:235], v137 offset:33792
	s_cmp_eq_u32 s8, 21
	s_cbranch_scc1 .Lt1_b_last
	s_mov_b32 m0, s78
	s_nop 0
	buffer_load_dwordx4 v244, s[4:7], s9 offen lds
	s_mov_b32 m0, s79
	s_nop 0
	buffer_load_dwordx4 v244, s[4:7], s10 offen lds
	s_waitcnt vmcnt(8)
	s_branch .Lt1_b_join
.Lt1_b_last:
	s_waitcnt vmcnt(2)
.Lt1_b_join:
	s_barrier
	s_waitcnt lgkmcnt(0)
	s_setprio 1
	s_waitcnt lgkmcnt(7)
	v_mfma_f32_16x16x32_bf16 v[28:31], v[72:75], v[184:187], v[28:31]
	v_mfma_f32_16x16x32_bf16 v[24:27], v[72:75], v[192:195], v[24:27]
	s_waitcnt lgkmcnt(5)
	v_mfma_f32_16x16x32_bf16 v[20:23], v[88:91], v[184:187], v[20:23]
	v_mfma_f32_16x16x32_bf16 v[16:19], v[88:91], v[192:195], v[16:19]
	s_waitcnt lgkmcnt(3)
	v_mfma_f32_16x16x32_bf16 v[12:15], v[196:199], v[184:187], v[12:15]
	v_mfma_f32_16x16x32_bf16 v[8:11], v[196:199], v[192:195], v[8:11]
	s_waitcnt lgkmcnt(1)
	v_mfma_f32_16x16x32_bf16 v[4:7], v[204:207], v[184:187], v[4:7]
	v_mfma_f32_16x16x32_bf16 v[0:3], v[204:207], v[192:195], v[0:3]
	v_mfma_f32_16x16x32_bf16 v[116:119], v[76:79], v[188:191], v[28:31]
	v_mfma_f32_16x16x32_bf16 v[112:115], v[76:79], v[138:141], v[24:27]
	v_mfma_f32_16x16x32_bf16 v[100:103], v[92:95], v[188:191], v[20:23]
	v_mfma_f32_16x16x32_bf16 v[96:99], v[92:95], v[138:141], v[16:19]
	v_mfma_f32_16x16x32_bf16 v[84:87], v[200:203], v[188:191], v[12:15]
	v_mfma_f32_16x16x32_bf16 v[80:83], v[200:203], v[138:141], v[8:11]
	s_waitcnt lgkmcnt(0)
	v_mfma_f32_16x16x32_bf16 v[68:71], v[232:235], v[188:191], v[4:7]
	v_mfma_f32_16x16x32_bf16 v[64:67], v[232:235], v[138:141], v[0:3]
	s_setprio 0
	s_barrier
	ds_read_b128 v[4:7], v142
	ds_read_b128 v[12:15], v142 offset:1024
	ds_read_b128 v[236:239], v142 offset:2048
	ds_read_b128 v[240:243], v142 offset:3072
	s_cmp_eq_u32 s8, 21
	s_cbranch_scc1 .Lt1_c_last
	s_mov_b32 m0, s81
	s_nop 0
	buffer_load_dwordx4 v244, s[56:59], s9 offen lds
	s_mov_b32 m0, s82
	s_nop 0
	buffer_load_dwordx4 v244, s[56:59], s10 offen lds
	s_waitcnt vmcnt(8)
	s_branch .Lt1_c_join

; #define LDA(dst, b, h)                                                                             \
;   _Pragma("unroll") for (int m = 0; m < 4; ++m) _Pragma("unroll") for (int k = 0; k < 2; ++k)      \
;       dst[m][k] = *reinterpret_cast<const bf16x8*>(SA(b, h) + lds_byte(wr * 64 + m * 16 + fr, k * 32 + fq * 8))
; #define LDB(dst, b, h)                                                                             \
;   _Pragma("unroll") for (int n = 0; n < 2; ++n) _Pragma("unroll") for (int k = 0; k < 2; ++k)      \
;       dst[n][k] = *reinterpret_cast<const bf16x8*>(SB(b, h) + lds_byte(wc * 32 + n * 16 + fr, k * 32 + fq * 8))
; #define WAIT_V(n) asm volatile("s_waitcnt vmcnt(" #n ")" ::: "memory")
; #define WAIT_L(n) asm volatile("s_waitcnt lgkmcnt(" #n ")" ::: "memory")
; #define BAR __builtin_amdgcn_s_barrier()
; template <bool PEEL = false>
; __device__ __forceinline__ void gemm_tile(f32x4 (&acc)[2][2][4][2], const u16* __restrict__ A, int lda,
;                                           const u16* __restrict__ B, int K) {
;     ...
;     LDB(B0, 1, 0); LDA(At, 1, 0); WAIT_V(2); BAR; WAIT_L(0); MMA(0, 0, At, B0); BAR;
;     LDB(B1, 1, 1); WAIT_V(0); BAR; WAIT_L(0); MMA(0, 1, At, B1); BAR;
;     LDA(At, 1, 1); BAR; WAIT_L(0); MMA(1, 0, At, B0); MMA(1, 1, At, B1); BAR;
;   }
;   if (wr == 0) BAR;
.Lt1_c_join:
	s_barrier
	s_waitcnt lgkmcnt(0)
	s_setprio 1
	s_waitcnt lgkmcnt(3)
	v_mfma_f32_16x16x32_bf16 v[0:3], v[72:75], v[4:7], v[60:63]
	s_waitcnt lgkmcnt(2)
	v_mfma_f32_16x16x32_bf16 v[124:127], v[76:79], v[12:15], v[0:3]
	s_waitcnt lgkmcnt(1)
	v_mfma_f32_16x16x32_bf16 v[0:3], v[72:75], v[236:239], v[56:59]
	s_waitcnt lgkmcnt(0)
	v_mfma_f32_16x16x32_bf16 v[120:123], v[76:79], v[240:243], v[0:3]
	v_mfma_f32_16x16x32_bf16 v[0:3], v[88:91], v[4:7], v[52:55]
	v_mfma_f32_16x16x32_bf16 v[108:111], v[92:95], v[12:15], v[0:3]
	v_mfma_f32_16x16x32_bf16 v[0:3], v[88:91], v[236:239], v[48:51]
	v_mfma_f32_16x16x32_bf16 v[104:107], v[92:95], v[240:243], v[0:3]
	v_mfma_f32_16x16x32_bf16 v[0:3], v[196:199], v[4:7], v[44:47]
	v_mfma_f32_16x16x32_bf16 v[92:95], v[200:203], v[12:15], v[0:3]
	v_mfma_f32_16x16x32_bf16 v[0:3], v[196:199], v[236:239], v[40:43]
	v_mfma_f32_16x16x32_bf16 v[88:91], v[200:203], v[240:243], v[0:3]
	v_mfma_f32_16x16x32_bf16 v[0:3], v[204:207], v[4:7], v[36:39]
	v_mfma_f32_16x16x32_bf16 v[76:79], v[232:235], v[12:15], v[0:3]
	v_mfma_f32_16x16x32_bf16 v[0:3], v[204:207], v[236:239], v[32:35]
	v_mfma_f32_16x16x32_bf16 v[72:75], v[232:235], v[240:243], v[0:3]
	s_setprio 0
	s_barrier
	ds_read_b128 v[24:27], v134 offset:49152
	ds_read_b128 v[28:31], v134 offset:50176
	ds_read_b128 v[36:39], v135 offset:49152
	ds_read_b128 v[196:199], v135 offset:50176
	ds_read_b128 v[200:203], v136 offset:49152
	ds_read_b128 v[204:207], v136 offset:50176
	ds_read_b128 v[232:235], v137 offset:49152
	ds_read_b128 v[134:137], v137 offset:50176
	s_cmp_eq_u32 s8, 21
	s_cbranch_scc1 .Lt1_d_skip
	s_add_i32 m0, s71, 0x18000
	s_nop 0
	buffer_load_dwordx4 v244, s[4:7], s11 offen lds
	s_add_i32 m0, s71, 0x1a000
	s_nop 0
	buffer_load_dwordx4 v244, s[4:7], s16 offen lds
	s_mov_b32 m0, s83
	s_nop 0
	buffer_load_dwordx4 v244, s[56:59], s11 offen lds
	s_mov_b32 m0, s84
	s_nop 0
	buffer_load_dwordx4 v244, s[56:59], s16 offen lds
.Lt1_d_skip:
	s_barrier
	s_waitcnt lgkmcnt(0)
	s_setprio 1
	s_waitcnt lgkmcnt(7)
	v_mfma_f32_16x16x32_bf16 v[0:3], v[24:27], v[184:187], v[208:211]
	s_waitcnt lgkmcnt(6)
	v_mfma_f32_16x16x32_bf16 v[52:55], v[28:31], v[188:191], v[0:3]
	v_mfma_f32_16x16x32_bf16 v[0:3], v[24:27], v[192:195], v[212:215]
	v_mfma_f32_16x16x32_bf16 v[48:51], v[28:31], v[138:141], v[0:3]
	s_waitcnt lgkmcnt(5)
	v_mfma_f32_16x16x32_bf16 v[0:3], v[36:39], v[184:187], v[216:219]
	s_waitcnt lgkmcnt(4)
	v_mfma_f32_16x16x32_bf16 v[40:43], v[196:199], v[188:191], v[0:3]
	v_mfma_f32_16x16x32_bf16 v[0:3], v[36:39], v[192:195], v[220:223]
	v_mfma_f32_16x16x32_bf16 v[32:35], v[196:199], v[138:141], v[0:3]
	s_waitcnt lgkmcnt(3)
	v_mfma_f32_16x16x32_bf16 v[0:3], v[200:203], v[184:187], v[224:227]
	s_waitcnt lgkmcnt(2)
	v_mfma_f32_16x16x32_bf16 v[20:23], v[204:207], v[188:191], v[0:3]
	v_mfma_f32_16x16x32_bf16 v[0:3], v[200:203], v[192:195], v[228:231]
	v_mfma_f32_16x16x32_bf16 v[16:19], v[204:207], v[138:141], v[0:3]
	s_waitcnt lgkmcnt(1)
	v_mfma_f32_16x16x32_bf16 v[0:3], v[232:235], v[184:187], v[144:147]
	s_waitcnt lgkmcnt(0)
	v_mfma_f32_16x16x32_bf16 v[8:11], v[134:137], v[188:191], v[0:3]
	v_mfma_f32_16x16x32_bf16 v[0:3], v[232:235], v[192:195], v[148:151]
	v_mfma_f32_16x16x32_bf16 v[0:3], v[134:137], v[138:141], v[0:3]
	s_setprio 0
	s_setprio 1
	v_mfma_f32_16x16x32_bf16 v[44:47], v[24:27], v[4:7], v[152:155]
	v_mfma_f32_16x16x32_bf16 v[24:27], v[24:27], v[236:239], v[156:159]
	v_mfma_f32_16x16x32_bf16 v[56:59], v[28:31], v[240:243], v[24:27]
	v_mfma_f32_16x16x32_bf16 v[24:27], v[36:39], v[4:7], v[160:163]
	v_mfma_f32_16x16x32_bf16 v[60:63], v[28:31], v[12:15], v[44:47]
	v_mfma_f32_16x16x32_bf16 v[44:47], v[196:199], v[12:15], v[24:27]
	v_mfma_f32_16x16x32_bf16 v[24:27], v[36:39], v[236:239], v[164:167]
	v_mfma_f32_16x16x32_bf16 v[36:39], v[196:199], v[240:243], v[24:27]
	v_mfma_f32_16x16x32_bf16 v[24:27], v[200:203], v[4:7], v[168:171]
	v_mfma_f32_16x16x32_bf16 v[4:7], v[232:235], v[4:7], v[176:179]
	v_mfma_f32_16x16x32_bf16 v[28:31], v[204:207], v[12:15], v[24:27]
	v_mfma_f32_16x16x32_bf16 v[24:27], v[200:203], v[236:239], v[172:175]
	v_mfma_f32_16x16x32_bf16 v[12:15], v[134:137], v[12:15], v[4:7]
	v_mfma_f32_16x16x32_bf16 v[4:7], v[232:235], v[236:239], v[180:183]
	v_mfma_f32_16x16x32_bf16 v[24:27], v[204:207], v[240:243], v[24:27]
	v_mfma_f32_16x16x32_bf16 v[4:7], v[134:137], v[240:243], v[4:7]
	s_setprio 0
	v_cmp_gt_u32_e32 vcc, s19, v133
	s_barrier
	s_and_saveexec_b64 s[0:1], vcc
	s_cbranch_execz .LBB0_135
	s_barrier
	s_branch .LBB0_135
